# down GEMM K-loop also uses scalar-base LDS-DMA loads (no VALU address adds); gate/up same; no setprio in GEMM loops
# baseline (speedup 1.0000x reference)
; #define PG8_STAGE(bufoff, gbase, voff) do { _Pragma("unroll") for (int _i = 0; _i < 2; ++_i) \
;         __builtin_amdgcn_global_load_lds((const unsigned*)((const char*)(gbase) + (voff)[_i]), (LAS unsigned*)(lds + (bufoff) + ldsw + _i * 8192), 16, 0, 0); } while (0)
; #define PG8_LDA(dst, b, h) do { _Pragma("unroll") for (int m = 0; m < 4; ++m) _Pragma("unroll") for (int k = 0; k < 2; ++k) dst[m][k] = *(const LAS bf16x8*)(pA + PG8_SA(b, h) + m * 2048 + k * 1024); } while (0)
; #define PG8_LDB(dst, b, h) do { _Pragma("unroll") for (int n = 0; n < 2; ++n) _Pragma("unroll") for (int k = 0; k < 2; ++k) dst[n][k] = *(const LAS bf16x8*)(pB + (PG8_SB(b, h) - 4 * HTB) + n * 2048 + k * 1024); } while (0)
; #define PG8_MMA(ai, bj, At, Bt) do { __builtin_amdgcn_s_setprio(1); _Pragma("unroll") for (int m = 0; m < 4; ++m) _Pragma("unroll") for (int n = 0; n < 2; ++n) _Pragma("unroll") for (int k = 0; k < 2; ++k) \
;         acc[ai][bj][m][n] = __builtin_amdgcn_mfma_f32_16x16x32_bf16(Bt[n][k], At[m][k], acc[ai][bj][m][n], 0, 0, 0); __builtin_amdgcn_s_setprio(0); } while (0)
; #define PG8_WAIT_V(n) asm volatile("s_waitcnt vmcnt(" #n ")" ::: "memory")
; #define PG8_WAIT_L(n) asm volatile("s_waitcnt lgkmcnt(" #n ")" ::: "memory")
; #define PG8_BAR __builtin_amdgcn_s_barrier()
; #define PG8_SCHED __builtin_amdgcn_sched_barrier(0)
; template <class Desc, class Epi, bool ALIGN_EPI>
; __device__ __forceinline__ void gemm_phase(LAS unsigned char* lds, const Desc& D, const Epi& E, int G, int c) {
;     ...
;             PG8_LDB(B0, 0, 0); PG8_LDB(B1, 0, 1); PG8_SCHED; PG8_LDA(At, 0, 0); PG8_STAGE(PG8_SA(1, 1), a1 + hstepA, voffA);
;             PG8_WAIT_V(8); PG8_WAIT_L(0); PG8_BAR; PG8_MMA(0, 0, At, B0); PG8_MMA(0, 1, At, B1); PG8_BAR; PG8_SCHED;
;             PG8_LDA(At, 0, 1); PG8_STAGE(PG8_SB(0, 0), b2, voffB); PG8_STAGE(PG8_SB(0, 1), b2 + hstepB, voffB); PG8_STAGE(PG8_SA(0, 0), a2, voffA);
;             PG8_WAIT_V(8); PG8_WAIT_L(0); PG8_BAR; PG8_MMA(1, 0, At, B0); PG8_MMA(1, 1, At, B1); PG8_BAR; PG8_SCHED;
.LBB0_1580:
	s_or_b32 s14, s30, 1
	s_add_i32 s30, s30, 2
	s_mov_b32 s31, s15
	s_lshl_b64 s[72:73], s[14:15], 7
	s_lshl_b64 s[74:75], s[30:31], 7
	s_add_u32 s14, s18, s74
	ds_read_b128 v[140:143], v163
	ds_read_b128 v[144:147], v163 offset:1024
	ds_read_b128 v[148:151], v163 offset:2048
	ds_read_b128 v[152:155], v163 offset:3072
	ds_read_b128 v[156:159], v163 offset:16384
	ds_read_b128 v[166:169], v163 offset:17408
	ds_read_b128 v[170:173], v163 offset:18432
	ds_read_b128 v[174:177], v163 offset:19456
	s_addc_u32 s31, s19, s75
	s_and_b64 s[46:47], s[34:35], exec
	s_cselect_b32 s47, s43, s31
	s_cselect_b32 s46, s42, s14
	s_add_u32 s14, s20, s74
	s_addc_u32 s31, s21, s75
	s_and_b64 s[34:35], s[34:35], exec
	s_cselect_b32 s35, s3, s31
	s_cselect_b32 s34, s13, s14
	s_add_u32 s14, s18, s72
	s_addc_u32 s31, s19, s73
	s_add_u32 s72, s14, 0x100000
	s_addc_u32 s73, s31, 0
	s_add_i32 m0, s52, 0xc000
	ds_read_b128 v[178:181], v162
	ds_read_b128 v[182:185], v162 offset:1024
	ds_read_b128 v[186:189], v162 offset:2048
	ds_read_b128 v[190:193], v162 offset:3072
	ds_read_b128 v[194:197], v162 offset:4096
	ds_read_b128 v[198:201], v162 offset:5120
	ds_read_b128 v[202:205], v162 offset:6144
	ds_read_b128 v[206:209], v162 offset:7168
	global_load_lds_dwordx4 v132, s[72:73]
	s_add_i32 m0, s52, 0xe000
	s_nop 0
	global_load_lds_dwordx4 v136, s[72:73]
	s_waitcnt vmcnt(8)
	s_waitcnt lgkmcnt(0)
	s_barrier
	v_mfma_f32_16x16x32_bf16 v[128:131], v[140:143], v[178:181], v[128:131]
	v_mfma_f32_16x16x32_bf16 v[124:127], v[148:151], v[178:181], v[124:127]
	v_mfma_f32_16x16x32_bf16 v[120:123], v[140:143], v[186:189], v[120:123]
	v_mfma_f32_16x16x32_bf16 v[116:119], v[148:151], v[186:189], v[116:119]
	v_mfma_f32_16x16x32_bf16 v[112:115], v[140:143], v[194:197], v[112:115]
	v_mfma_f32_16x16x32_bf16 v[108:111], v[148:151], v[194:197], v[108:111]
	v_mfma_f32_16x16x32_bf16 v[104:107], v[140:143], v[202:205], v[104:107]
	v_mfma_f32_16x16x32_bf16 v[100:103], v[148:151], v[202:205], v[100:103]
	v_mfma_f32_16x16x32_bf16 v[128:131], v[144:147], v[182:185], v[128:131]
	v_mfma_f32_16x16x32_bf16 v[124:127], v[152:155], v[182:185], v[124:127]
	v_mfma_f32_16x16x32_bf16 v[120:123], v[144:147], v[190:193], v[120:123]
	v_mfma_f32_16x16x32_bf16 v[116:119], v[152:155], v[190:193], v[116:119]
	v_mfma_f32_16x16x32_bf16 v[112:115], v[144:147], v[198:201], v[112:115]
	v_mfma_f32_16x16x32_bf16 v[108:111], v[152:155], v[198:201], v[108:111]
	v_mfma_f32_16x16x32_bf16 v[104:107], v[144:147], v[206:209], v[104:107]
	v_mfma_f32_16x16x32_bf16 v[100:103], v[152:155], v[206:209], v[100:103]
	v_mfma_f32_16x16x32_bf16 v[96:99], v[156:159], v[178:181], v[96:99]
	v_mfma_f32_16x16x32_bf16 v[92:95], v[170:173], v[178:181], v[92:95]
	v_mfma_f32_16x16x32_bf16 v[88:91], v[156:159], v[186:189], v[88:91]
	v_mfma_f32_16x16x32_bf16 v[84:87], v[170:173], v[186:189], v[84:87]
	v_mfma_f32_16x16x32_bf16 v[80:83], v[156:159], v[194:197], v[80:83]
	v_mfma_f32_16x16x32_bf16 v[76:79], v[170:173], v[194:197], v[76:79]
	v_mfma_f32_16x16x32_bf16 v[72:75], v[156:159], v[202:205], v[72:75]
	v_mfma_f32_16x16x32_bf16 v[68:71], v[170:173], v[202:205], v[68:71]
	v_mfma_f32_16x16x32_bf16 v[96:99], v[166:169], v[182:185], v[96:99]
	v_mfma_f32_16x16x32_bf16 v[92:95], v[174:177], v[182:185], v[92:95]
	v_mfma_f32_16x16x32_bf16 v[88:91], v[166:169], v[190:193], v[88:91]
	v_mfma_f32_16x16x32_bf16 v[84:87], v[174:177], v[190:193], v[84:87]
	v_mfma_f32_16x16x32_bf16 v[80:83], v[166:169], v[198:201], v[80:83]
	v_mfma_f32_16x16x32_bf16 v[76:79], v[174:177], v[198:201], v[76:79]
	v_mfma_f32_16x16x32_bf16 v[72:75], v[166:169], v[206:209], v[72:75]
	v_mfma_f32_16x16x32_bf16 v[68:71], v[174:177], v[206:209], v[68:71]
	s_barrier
	s_mov_b32 m0, s53
	s_add_u32 s72, s34, 0x100000
	s_addc_u32 s73, s35, 0
	ds_read_b128 v[178:181], v162 offset:16384
	ds_read_b128 v[182:185], v162 offset:17408
	ds_read_b128 v[186:189], v162 offset:18432
	ds_read_b128 v[190:193], v162 offset:19456
	ds_read_b128 v[194:197], v162 offset:20480
	ds_read_b128 v[198:201], v162 offset:21504
	ds_read_b128 v[202:205], v162 offset:22528
	ds_read_b128 v[206:209], v162 offset:23552
	global_load_lds_dwordx4 v134, s[34:35]
	s_mov_b32 m0, s54
	s_nop 0
	global_load_lds_dwordx4 v138, s[34:35]
	s_mov_b32 m0, s55
	s_nop 0
	global_load_lds_dwordx4 v134, s[72:73]
	s_mov_b32 m0, s56
	s_nop 0
	global_load_lds_dwordx4 v138, s[72:73]
	s_mov_b32 m0, s52
	s_nop 0
	global_load_lds_dwordx4 v132, s[46:47]
	s_mov_b32 m0, s57
	s_nop 0
	global_load_lds_dwordx4 v136, s[46:47]
	s_waitcnt vmcnt(8)
	s_waitcnt lgkmcnt(0)
	s_barrier
; #define PG8_STAGE(bufoff, gbase, voff) do { _Pragma("unroll") for (int _i = 0; _i < 2; ++_i) \
;         __builtin_amdgcn_global_load_lds((const unsigned*)((const char*)(gbase) + (voff)[_i]), (LAS unsigned*)(lds + (bufoff) + ldsw + _i * 8192), 16, 0, 0); } while (0)
; #define PG8_LDA(dst, b, h) do { _Pragma("unroll") for (int m = 0; m < 4; ++m) _Pragma("unroll") for (int k = 0; k < 2; ++k) dst[m][k] = *(const LAS bf16x8*)(pA + PG8_SA(b, h) + m * 2048 + k * 1024); } while (0)
; #define PG8_LDB(dst, b, h) do { _Pragma("unroll") for (int n = 0; n < 2; ++n) _Pragma("unroll") for (int k = 0; k < 2; ++k) dst[n][k] = *(const LAS bf16x8*)(pB + (PG8_SB(b, h) - 4 * HTB) + n * 2048 + k * 1024); } while (0)
; #define PG8_MMA(ai, bj, At, Bt) do { __builtin_amdgcn_s_setprio(1); _Pragma("unroll") for (int m = 0; m < 4; ++m) _Pragma("unroll") for (int n = 0; n < 2; ++n) _Pragma("unroll") for (int k = 0; k < 2; ++k) \
;         acc[ai][bj][m][n] = __builtin_amdgcn_mfma_f32_16x16x32_bf16(Bt[n][k], At[m][k], acc[ai][bj][m][n], 0, 0, 0); __builtin_amdgcn_s_setprio(0); } while (0)
; #define PG8_WAIT_V(n) asm volatile("s_waitcnt vmcnt(" #n ")" ::: "memory")
; #define PG8_WAIT_L(n) asm volatile("s_waitcnt lgkmcnt(" #n ")" ::: "memory")
; #define PG8_BAR __builtin_amdgcn_s_barrier()
; #define PG8_SCHED __builtin_amdgcn_sched_barrier(0)
; template <class Desc, class Epi, bool ALIGN_EPI>
; __device__ __forceinline__ void gemm_phase(LAS unsigned char* lds, const Desc& D, const Epi& E, int G, int c) {
;     ...
;             PG8_WAIT_V(8); PG8_WAIT_L(0); PG8_BAR; PG8_MMA(1, 0, At, B0); PG8_MMA(1, 1, At, B1); PG8_BAR; PG8_SCHED;
;             PG8_LDB(B0, 1, 0); PG8_LDB(B1, 1, 1); PG8_SCHED; PG8_LDA(At, 1, 0); PG8_STAGE(PG8_SA(0, 1), a2 + hstepA, voffA);
;             PG8_WAIT_V(8); PG8_WAIT_L(0); PG8_BAR; PG8_MMA(0, 0, At, B0); PG8_MMA(0, 1, At, B1); PG8_BAR; PG8_SCHED;
	v_mfma_f32_16x16x32_bf16 v[64:67], v[140:143], v[178:181], v[64:67]
	v_mfma_f32_16x16x32_bf16 v[52:55], v[148:151], v[178:181], v[52:55]
	v_mfma_f32_16x16x32_bf16 v[32:35], v[140:143], v[186:189], v[32:35]
	v_mfma_f32_16x16x32_bf16 v[20:23], v[148:151], v[186:189], v[20:23]
	v_mfma_f32_16x16x32_bf16 v[16:19], v[140:143], v[194:197], v[16:19]
	v_mfma_f32_16x16x32_bf16 v[12:15], v[148:151], v[194:197], v[12:15]
	v_mfma_f32_16x16x32_bf16 v[8:11], v[140:143], v[202:205], v[8:11]
	v_mfma_f32_16x16x32_bf16 v[4:7], v[148:151], v[202:205], v[4:7]
	v_mfma_f32_16x16x32_bf16 v[64:67], v[144:147], v[182:185], v[64:67]
	v_mfma_f32_16x16x32_bf16 v[52:55], v[152:155], v[182:185], v[52:55]
	v_mfma_f32_16x16x32_bf16 v[32:35], v[144:147], v[190:193], v[32:35]
	v_mfma_f32_16x16x32_bf16 v[20:23], v[152:155], v[190:193], v[20:23]
	v_mfma_f32_16x16x32_bf16 v[16:19], v[144:147], v[198:201], v[16:19]
	v_mfma_f32_16x16x32_bf16 v[12:15], v[152:155], v[198:201], v[12:15]
	v_mfma_f32_16x16x32_bf16 v[8:11], v[144:147], v[206:209], v[8:11]
	v_mfma_f32_16x16x32_bf16 v[4:7], v[152:155], v[206:209], v[4:7]
	v_mfma_f32_16x16x32_bf16 v[60:63], v[156:159], v[178:181], v[60:63]
	v_mfma_f32_16x16x32_bf16 v[56:59], v[170:173], v[178:181], v[56:59]
	v_mfma_f32_16x16x32_bf16 v[48:51], v[156:159], v[186:189], v[48:51]
	v_mfma_f32_16x16x32_bf16 v[44:47], v[170:173], v[186:189], v[44:47]
	v_mfma_f32_16x16x32_bf16 v[40:43], v[156:159], v[194:197], v[40:43]
	v_mfma_f32_16x16x32_bf16 v[36:39], v[170:173], v[194:197], v[36:39]
	v_mfma_f32_16x16x32_bf16 v[28:31], v[156:159], v[202:205], v[28:31]
	v_mfma_f32_16x16x32_bf16 v[24:27], v[170:173], v[202:205], v[24:27]
	v_mfma_f32_16x16x32_bf16 v[60:63], v[166:169], v[182:185], v[60:63]
	v_mfma_f32_16x16x32_bf16 v[56:59], v[174:177], v[182:185], v[56:59]
	v_mfma_f32_16x16x32_bf16 v[48:51], v[166:169], v[190:193], v[48:51]
	v_mfma_f32_16x16x32_bf16 v[44:47], v[174:177], v[190:193], v[44:47]
	v_mfma_f32_16x16x32_bf16 v[40:43], v[166:169], v[198:201], v[40:43]
	v_mfma_f32_16x16x32_bf16 v[36:39], v[174:177], v[198:201], v[36:39]
	v_mfma_f32_16x16x32_bf16 v[28:31], v[166:169], v[206:209], v[28:31]
	v_mfma_f32_16x16x32_bf16 v[24:27], v[174:177], v[206:209], v[24:27]
	s_barrier
	ds_read_b128 v[140:143], v163 offset:32768
	ds_read_b128 v[144:147], v163 offset:33792
	ds_read_b128 v[148:151], v163 offset:34816
	ds_read_b128 v[152:155], v163 offset:35840
	ds_read_b128 v[156:159], v163 offset:49152
	ds_read_b128 v[166:169], v163 offset:50176
	ds_read_b128 v[170:173], v163 offset:51200
	ds_read_b128 v[174:177], v163 offset:52224
	s_add_u32 s46, s46, 0x100000
	s_addc_u32 s47, s47, 0
	s_mov_b32 m0, s58
	ds_read_b128 v[178:181], v162 offset:32768
	ds_read_b128 v[182:185], v162 offset:33792
	ds_read_b128 v[186:189], v162 offset:34816
	ds_read_b128 v[190:193], v162 offset:35840
	ds_read_b128 v[194:197], v162 offset:36864
	ds_read_b128 v[198:201], v162 offset:37888
	ds_read_b128 v[202:205], v162 offset:38912
	ds_read_b128 v[206:209], v162 offset:39936
	global_load_lds_dwordx4 v132, s[46:47]
	s_mov_b32 m0, s59
	s_nop 0
	global_load_lds_dwordx4 v136, s[46:47]
	s_waitcnt vmcnt(8)
	s_waitcnt lgkmcnt(0)
	s_barrier
	v_mfma_f32_16x16x32_bf16 v[128:131], v[140:143], v[178:181], v[128:131]
	v_mfma_f32_16x16x32_bf16 v[124:127], v[148:151], v[178:181], v[124:127]
	v_mfma_f32_16x16x32_bf16 v[120:123], v[140:143], v[186:189], v[120:123]
	v_mfma_f32_16x16x32_bf16 v[116:119], v[148:151], v[186:189], v[116:119]
	v_mfma_f32_16x16x32_bf16 v[112:115], v[140:143], v[194:197], v[112:115]
	v_mfma_f32_16x16x32_bf16 v[108:111], v[148:151], v[194:197], v[108:111]
	v_mfma_f32_16x16x32_bf16 v[104:107], v[140:143], v[202:205], v[104:107]
	v_mfma_f32_16x16x32_bf16 v[100:103], v[148:151], v[202:205], v[100:103]
	v_mfma_f32_16x16x32_bf16 v[128:131], v[144:147], v[182:185], v[128:131]
	v_mfma_f32_16x16x32_bf16 v[124:127], v[152:155], v[182:185], v[124:127]
	v_mfma_f32_16x16x32_bf16 v[120:123], v[144:147], v[190:193], v[120:123]
	v_mfma_f32_16x16x32_bf16 v[116:119], v[152:155], v[190:193], v[116:119]
	v_mfma_f32_16x16x32_bf16 v[112:115], v[144:147], v[198:201], v[112:115]
	v_mfma_f32_16x16x32_bf16 v[108:111], v[152:155], v[198:201], v[108:111]
	v_mfma_f32_16x16x32_bf16 v[104:107], v[144:147], v[206:209], v[104:107]
	v_mfma_f32_16x16x32_bf16 v[100:103], v[152:155], v[206:209], v[100:103]
	v_mfma_f32_16x16x32_bf16 v[96:99], v[156:159], v[178:181], v[96:99]
	v_mfma_f32_16x16x32_bf16 v[92:95], v[170:173], v[178:181], v[92:95]
	v_mfma_f32_16x16x32_bf16 v[88:91], v[156:159], v[186:189], v[88:91]
	v_mfma_f32_16x16x32_bf16 v[84:87], v[170:173], v[186:189], v[84:87]
	v_mfma_f32_16x16x32_bf16 v[80:83], v[156:159], v[194:197], v[80:83]
	v_mfma_f32_16x16x32_bf16 v[76:79], v[170:173], v[194:197], v[76:79]
	v_mfma_f32_16x16x32_bf16 v[72:75], v[156:159], v[202:205], v[72:75]
	v_mfma_f32_16x16x32_bf16 v[68:71], v[170:173], v[202:205], v[68:71]
	v_mfma_f32_16x16x32_bf16 v[96:99], v[166:169], v[182:185], v[96:99]
	v_mfma_f32_16x16x32_bf16 v[92:95], v[174:177], v[182:185], v[92:95]
	v_mfma_f32_16x16x32_bf16 v[88:91], v[166:169], v[190:193], v[88:91]
	v_mfma_f32_16x16x32_bf16 v[84:87], v[174:177], v[190:193], v[84:87]
	v_mfma_f32_16x16x32_bf16 v[80:83], v[166:169], v[198:201], v[80:83]
	v_mfma_f32_16x16x32_bf16 v[76:79], v[174:177], v[198:201], v[76:79]
	v_mfma_f32_16x16x32_bf16 v[72:75], v[166:169], v[206:209], v[72:75]
	v_mfma_f32_16x16x32_bf16 v[68:71], v[174:177], v[206:209], v[68:71]
	s_barrier
; #define PG8_STAGE(bufoff, gbase, voff) do { _Pragma("unroll") for (int _i = 0; _i < 2; ++_i) \
;         __builtin_amdgcn_global_load_lds((const unsigned*)((const char*)(gbase) + (voff)[_i]), (LAS unsigned*)(lds + (bufoff) + ldsw + _i * 8192), 16, 0, 0); } while (0)
; #define PG8_LDA(dst, b, h) do { _Pragma("unroll") for (int m = 0; m < 4; ++m) _Pragma("unroll") for (int k = 0; k < 2; ++k) dst[m][k] = *(const LAS bf16x8*)(pA + PG8_SA(b, h) + m * 2048 + k * 1024); } while (0)
; #define PG8_MMA(ai, bj, At, Bt) do { __builtin_amdgcn_s_setprio(1); _Pragma("unroll") for (int m = 0; m < 4; ++m) _Pragma("unroll") for (int n = 0; n < 2; ++n) _Pragma("unroll") for (int k = 0; k < 2; ++k) \
;         acc[ai][bj][m][n] = __builtin_amdgcn_mfma_f32_16x16x32_bf16(Bt[n][k], At[m][k], acc[ai][bj][m][n], 0, 0, 0); __builtin_amdgcn_s_setprio(0); } while (0)
; #define PG8_WAIT_V(n) asm volatile("s_waitcnt vmcnt(" #n ")" ::: "memory")
; #define PG8_WAIT_L(n) asm volatile("s_waitcnt lgkmcnt(" #n ")" ::: "memory")
; #define PG8_BAR __builtin_amdgcn_s_barrier()
; #define PG8_SCHED __builtin_amdgcn_sched_barrier(0)
; template <class Desc, class Epi, bool ALIGN_EPI>
; __device__ __forceinline__ void gemm_phase(LAS unsigned char* lds, const Desc& D, const Epi& E, int G, int c) {
;     ...
;             PG8_LDA(At, 1, 1); PG8_STAGE(PG8_SB(1, 0), b3, voffB); PG8_STAGE(PG8_SB(1, 1), b3 + hstepB, voffB); PG8_STAGE(PG8_SA(1, 0), a3, voffA);
;             PG8_WAIT_V(8); PG8_WAIT_L(0); PG8_BAR; PG8_MMA(1, 0, At, B0); PG8_MMA(1, 1, At, B1); PG8_BAR; PG8_SCHED;
	s_mov_b32 m0, s61
	s_add_u32 s72, s34, 0x80
	s_addc_u32 s73, s35, 0
	s_add_u32 s34, s34, 0x100080
	s_addc_u32 s35, s35, 0
	ds_read_b128 v[178:181], v162 offset:49152
	ds_read_b128 v[182:185], v162 offset:50176
	ds_read_b128 v[186:189], v162 offset:51200
	ds_read_b128 v[190:193], v162 offset:52224
	ds_read_b128 v[194:197], v162 offset:53248
	ds_read_b128 v[198:201], v162 offset:54272
	ds_read_b128 v[202:205], v162 offset:55296
	ds_read_b128 v[206:209], v162 offset:56320
	global_load_lds_dwordx4 v134, s[72:73]
	s_mov_b32 m0, s62
	s_nop 0
	global_load_lds_dwordx4 v138, s[72:73]
	s_mov_b32 m0, s65
	s_nop 0
	global_load_lds_dwordx4 v134, s[34:35]
	s_mov_b32 m0, s67
	s_nop 0
	global_load_lds_dwordx4 v138, s[34:35]
	s_sub_u32 s74, s46, 0xfff80
	s_subb_u32 s75, s47, 0
	s_mov_b32 m0, s63
	s_nop 0
	global_load_lds_dwordx4 v132, s[74:75]
	s_mov_b32 m0, s64
	s_nop 0
	global_load_lds_dwordx4 v136, s[74:75]
	s_waitcnt vmcnt(8)
	s_waitcnt lgkmcnt(0)
	s_barrier
	v_mfma_f32_16x16x32_bf16 v[64:67], v[140:143], v[178:181], v[64:67]
	v_mfma_f32_16x16x32_bf16 v[52:55], v[148:151], v[178:181], v[52:55]
	v_mfma_f32_16x16x32_bf16 v[32:35], v[140:143], v[186:189], v[32:35]
	v_mfma_f32_16x16x32_bf16 v[20:23], v[148:151], v[186:189], v[20:23]
	v_mfma_f32_16x16x32_bf16 v[16:19], v[140:143], v[194:197], v[16:19]
	v_mfma_f32_16x16x32_bf16 v[12:15], v[148:151], v[194:197], v[12:15]
	v_mfma_f32_16x16x32_bf16 v[8:11], v[140:143], v[202:205], v[8:11]
	v_mfma_f32_16x16x32_bf16 v[4:7], v[148:151], v[202:205], v[4:7]
	v_mfma_f32_16x16x32_bf16 v[64:67], v[144:147], v[182:185], v[64:67]
	v_mfma_f32_16x16x32_bf16 v[52:55], v[152:155], v[182:185], v[52:55]
	v_mfma_f32_16x16x32_bf16 v[32:35], v[144:147], v[190:193], v[32:35]
	v_mfma_f32_16x16x32_bf16 v[20:23], v[152:155], v[190:193], v[20:23]
	v_mfma_f32_16x16x32_bf16 v[16:19], v[144:147], v[198:201], v[16:19]
	v_mfma_f32_16x16x32_bf16 v[12:15], v[152:155], v[198:201], v[12:15]
	v_mfma_f32_16x16x32_bf16 v[8:11], v[144:147], v[206:209], v[8:11]
	v_mfma_f32_16x16x32_bf16 v[4:7], v[152:155], v[206:209], v[4:7]
	v_mfma_f32_16x16x32_bf16 v[60:63], v[156:159], v[178:181], v[60:63]
	v_mfma_f32_16x16x32_bf16 v[56:59], v[170:173], v[178:181], v[56:59]
	v_mfma_f32_16x16x32_bf16 v[48:51], v[156:159], v[186:189], v[48:51]
	v_mfma_f32_16x16x32_bf16 v[44:47], v[170:173], v[186:189], v[44:47]
	v_mfma_f32_16x16x32_bf16 v[40:43], v[156:159], v[194:197], v[40:43]
	v_mfma_f32_16x16x32_bf16 v[36:39], v[170:173], v[194:197], v[36:39]
	v_mfma_f32_16x16x32_bf16 v[28:31], v[156:159], v[202:205], v[28:31]
	v_mfma_f32_16x16x32_bf16 v[24:27], v[170:173], v[202:205], v[24:27]
	v_mfma_f32_16x16x32_bf16 v[60:63], v[166:169], v[182:185], v[60:63]
	v_mfma_f32_16x16x32_bf16 v[56:59], v[174:177], v[182:185], v[56:59]
	v_mfma_f32_16x16x32_bf16 v[48:51], v[166:169], v[190:193], v[48:51]
	v_mfma_f32_16x16x32_bf16 v[44:47], v[174:177], v[190:193], v[44:47]
	v_mfma_f32_16x16x32_bf16 v[40:43], v[166:169], v[198:201], v[40:43]
	v_mfma_f32_16x16x32_bf16 v[36:39], v[174:177], v[198:201], v[36:39]
	v_mfma_f32_16x16x32_bf16 v[28:31], v[166:169], v[206:209], v[28:31]
	v_mfma_f32_16x16x32_bf16 v[24:27], v[174:177], v[206:209], v[24:27]
	s_barrier
	s_cmp_ge_u32 s30, s2
	s_cbranch_scc1 .LBB0_1591

; #define PG8_STAGE(bufoff, gbase, voff) do { _Pragma("unroll") for (int _i = 0; _i < 2; ++_i) \
;         __builtin_amdgcn_global_load_lds((const unsigned*)((const char*)(gbase) + (voff)[_i]), (LAS unsigned*)(lds + (bufoff) + ldsw + _i * 8192), 16, 0, 0); } while (0)
; #define PG8_LDA(dst, b, h) do { _Pragma("unroll") for (int m = 0; m < 4; ++m) _Pragma("unroll") for (int k = 0; k < 2; ++k) dst[m][k] = *(const LAS bf16x8*)(pA + PG8_SA(b, h) + m * 2048 + k * 1024); } while (0)
; #define PG8_LDB(dst, b, h) do { _Pragma("unroll") for (int n = 0; n < 2; ++n) _Pragma("unroll") for (int k = 0; k < 2; ++k) dst[n][k] = *(const LAS bf16x8*)(pB + (PG8_SB(b, h) - 4 * HTB) + n * 2048 + k * 1024); } while (0)
; #define PG8_MMA(ai, bj, At, Bt) do { __builtin_amdgcn_s_setprio(1); _Pragma("unroll") for (int m = 0; m < 4; ++m) _Pragma("unroll") for (int n = 0; n < 2; ++n) _Pragma("unroll") for (int k = 0; k < 2; ++k) \
;         acc[ai][bj][m][n] = __builtin_amdgcn_mfma_f32_16x16x32_bf16(Bt[n][k], At[m][k], acc[ai][bj][m][n], 0, 0, 0); __builtin_amdgcn_s_setprio(0); } while (0)
; #define PG8_WAIT_V(n) asm volatile("s_waitcnt vmcnt(" #n ")" ::: "memory")
; #define PG8_WAIT_L(n) asm volatile("s_waitcnt lgkmcnt(" #n ")" ::: "memory")
; #define PG8_BAR __builtin_amdgcn_s_barrier()
; #define PG8_SCHED __builtin_amdgcn_sched_barrier(0)
; template <class Desc, class Epi, bool ALIGN_EPI>
; __device__ __forceinline__ void gemm_phase(LAS unsigned char* lds, const Desc& D, const Epi& E, int G, int c) {
;     ...
;             PG8_LDB(B0, 0, 0); PG8_LDB(B1, 0, 1); PG8_SCHED; PG8_LDA(At, 0, 0); PG8_STAGE(PG8_SA(1, 1), a1 + hstepA, voffA);
;             PG8_WAIT_V(8); PG8_WAIT_L(0); PG8_BAR; PG8_MMA(0, 0, At, B0); PG8_MMA(0, 1, At, B1); PG8_BAR; PG8_SCHED;
;             PG8_LDA(At, 0, 1); PG8_STAGE(PG8_SB(0, 0), b2, voffB); PG8_STAGE(PG8_SB(0, 1), b2 + hstepB, voffB); PG8_STAGE(PG8_SA(0, 0), a2, voffA);
.LBB0_1765:
	s_or_b32 s14, s39, 1
	s_lshl_b64 s[40:41], s[14:15], 7
	s_add_i32 s14, s39, 2
	s_lshl_b64 s[42:43], s[14:15], 7
	s_add_u32 s39, s12, s42
	s_waitcnt lgkmcnt(0)
	ds_read_b128 v[132:135], v248
	ds_read_b128 v[136:139], v248 offset:1024
	ds_read_b128 v[140:143], v248 offset:2048
	ds_read_b128 v[144:147], v248 offset:3072
	ds_read_b128 v[148:151], v248 offset:16384
	ds_read_b128 v[152:155], v248 offset:17408
	ds_read_b128 v[156:159], v248 offset:18432
	ds_read_b128 v[160:163], v248 offset:19456
	s_addc_u32 s78, s13, s43
	s_and_b64 s[30:31], s[20:21], exec
	s_cselect_b32 s31, s49, s78
	s_cselect_b32 s30, s48, s39
	s_add_u32 s39, s16, s42
	s_addc_u32 s42, s17, s43
	s_and_b64 s[20:21], s[20:21], exec
	s_cselect_b32 s21, s51, s42
	s_cselect_b32 s20, s50, s39
	s_add_u32 s39, s12, s40
	s_addc_u32 s41, s13, s41
	s_add_u32 s40, s39, 0x2b0000
	s_addc_u32 s41, s41, 0
	s_add_i32 m0, s56, 0xc000
	ds_read_b128 v[164:167], v247
	ds_read_b128 v[168:171], v247 offset:1024
	ds_read_b128 v[172:175], v247 offset:2048
	ds_read_b128 v[176:179], v247 offset:3072
	ds_read_b128 v[180:183], v247 offset:4096
	ds_read_b128 v[184:187], v247 offset:5120
	ds_read_b128 v[188:191], v247 offset:6144
	ds_read_b128 v[192:195], v247 offset:7168
	global_load_lds_dwordx4 v200, s[40:41]
	s_add_i32 m0, s56, 0xe000
	s_nop 0
	global_load_lds_dwordx4 v204, s[40:41]
	s_waitcnt vmcnt(8)
	s_waitcnt lgkmcnt(0)
	s_barrier
	v_mfma_f32_16x16x32_bf16 v[128:131], v[132:135], v[164:167], v[128:131]
	v_mfma_f32_16x16x32_bf16 v[124:127], v[140:143], v[164:167], v[124:127]
	v_mfma_f32_16x16x32_bf16 v[120:123], v[132:135], v[172:175], v[120:123]
	v_mfma_f32_16x16x32_bf16 v[116:119], v[140:143], v[172:175], v[116:119]
	v_mfma_f32_16x16x32_bf16 v[112:115], v[132:135], v[180:183], v[112:115]
	v_mfma_f32_16x16x32_bf16 v[108:111], v[140:143], v[180:183], v[108:111]
	v_mfma_f32_16x16x32_bf16 v[104:107], v[132:135], v[188:191], v[104:107]
	v_mfma_f32_16x16x32_bf16 v[100:103], v[140:143], v[188:191], v[100:103]
	v_mfma_f32_16x16x32_bf16 v[128:131], v[136:139], v[168:171], v[128:131]
	v_mfma_f32_16x16x32_bf16 v[124:127], v[144:147], v[168:171], v[124:127]
	v_mfma_f32_16x16x32_bf16 v[120:123], v[136:139], v[176:179], v[120:123]
	v_mfma_f32_16x16x32_bf16 v[116:119], v[144:147], v[176:179], v[116:119]
	v_mfma_f32_16x16x32_bf16 v[112:115], v[136:139], v[184:187], v[112:115]
	v_mfma_f32_16x16x32_bf16 v[108:111], v[144:147], v[184:187], v[108:111]
	v_mfma_f32_16x16x32_bf16 v[104:107], v[136:139], v[192:195], v[104:107]
	v_mfma_f32_16x16x32_bf16 v[100:103], v[144:147], v[192:195], v[100:103]
	v_mfma_f32_16x16x32_bf16 v[96:99], v[148:151], v[164:167], v[96:99]
	v_mfma_f32_16x16x32_bf16 v[92:95], v[156:159], v[164:167], v[92:95]
	v_mfma_f32_16x16x32_bf16 v[88:91], v[148:151], v[172:175], v[88:91]
	v_mfma_f32_16x16x32_bf16 v[80:83], v[156:159], v[172:175], v[80:83]
	v_mfma_f32_16x16x32_bf16 v[64:67], v[148:151], v[180:183], v[64:67]
	v_mfma_f32_16x16x32_bf16 v[52:55], v[156:159], v[180:183], v[52:55]
	v_mfma_f32_16x16x32_bf16 v[32:35], v[148:151], v[188:191], v[32:35]
	v_mfma_f32_16x16x32_bf16 v[20:23], v[156:159], v[188:191], v[20:23]
	v_mfma_f32_16x16x32_bf16 v[96:99], v[152:155], v[168:171], v[96:99]
	v_mfma_f32_16x16x32_bf16 v[92:95], v[160:163], v[168:171], v[92:95]
	v_mfma_f32_16x16x32_bf16 v[88:91], v[152:155], v[176:179], v[88:91]
	v_mfma_f32_16x16x32_bf16 v[80:83], v[160:163], v[176:179], v[80:83]
	v_mfma_f32_16x16x32_bf16 v[64:67], v[152:155], v[184:187], v[64:67]
	v_mfma_f32_16x16x32_bf16 v[52:55], v[160:163], v[184:187], v[52:55]
	v_mfma_f32_16x16x32_bf16 v[32:35], v[152:155], v[192:195], v[32:35]
	v_mfma_f32_16x16x32_bf16 v[20:23], v[160:163], v[192:195], v[20:23]
	s_barrier
	s_mov_b32 m0, s57
	s_add_u32 s40, s20, 0x2b0000
	s_addc_u32 s41, s21, 0
	ds_read_b128 v[164:167], v247 offset:16384
	ds_read_b128 v[168:171], v247 offset:17408
	ds_read_b128 v[172:175], v247 offset:18432
	ds_read_b128 v[176:179], v247 offset:19456
	ds_read_b128 v[180:183], v247 offset:20480
	ds_read_b128 v[184:187], v247 offset:21504
	ds_read_b128 v[188:191], v247 offset:22528
	ds_read_b128 v[192:195], v247 offset:23552
	global_load_lds_dwordx4 v202, s[20:21]
	s_mov_b32 m0, s58
	s_nop 0
	global_load_lds_dwordx4 v206, s[20:21]
	s_mov_b32 m0, s59
	s_nop 0
	global_load_lds_dwordx4 v202, s[40:41]
	s_mov_b32 m0, s60
	s_nop 0
	global_load_lds_dwordx4 v206, s[40:41]
	s_mov_b32 m0, s56
	s_nop 0
	global_load_lds_dwordx4 v200, s[30:31]
	s_mov_b32 m0, s61
	s_nop 0
	global_load_lds_dwordx4 v204, s[30:31]
	s_waitcnt vmcnt(8)
	s_waitcnt lgkmcnt(0)
	s_barrier
; #define PG8_STAGE(bufoff, gbase, voff) do { _Pragma("unroll") for (int _i = 0; _i < 2; ++_i) \
;         __builtin_amdgcn_global_load_lds((const unsigned*)((const char*)(gbase) + (voff)[_i]), (LAS unsigned*)(lds + (bufoff) + ldsw + _i * 8192), 16, 0, 0); } while (0)
; #define PG8_LDA(dst, b, h) do { _Pragma("unroll") for (int m = 0; m < 4; ++m) _Pragma("unroll") for (int k = 0; k < 2; ++k) dst[m][k] = *(const LAS bf16x8*)(pA + PG8_SA(b, h) + m * 2048 + k * 1024); } while (0)
; #define PG8_LDB(dst, b, h) do { _Pragma("unroll") for (int n = 0; n < 2; ++n) _Pragma("unroll") for (int k = 0; k < 2; ++k) dst[n][k] = *(const LAS bf16x8*)(pB + (PG8_SB(b, h) - 4 * HTB) + n * 2048 + k * 1024); } while (0)
; #define PG8_MMA(ai, bj, At, Bt) do { __builtin_amdgcn_s_setprio(1); _Pragma("unroll") for (int m = 0; m < 4; ++m) _Pragma("unroll") for (int n = 0; n < 2; ++n) _Pragma("unroll") for (int k = 0; k < 2; ++k) \
;         acc[ai][bj][m][n] = __builtin_amdgcn_mfma_f32_16x16x32_bf16(Bt[n][k], At[m][k], acc[ai][bj][m][n], 0, 0, 0); __builtin_amdgcn_s_setprio(0); } while (0)
; #define PG8_WAIT_V(n) asm volatile("s_waitcnt vmcnt(" #n ")" ::: "memory")
; #define PG8_WAIT_L(n) asm volatile("s_waitcnt lgkmcnt(" #n ")" ::: "memory")
; #define PG8_BAR __builtin_amdgcn_s_barrier()
; #define PG8_SCHED __builtin_amdgcn_sched_barrier(0)
; template <class Desc, class Epi, bool ALIGN_EPI>
; __device__ __forceinline__ void gemm_phase(LAS unsigned char* lds, const Desc& D, const Epi& E, int G, int c) {
;     ...
;             PG8_WAIT_V(8); PG8_WAIT_L(0); PG8_BAR; PG8_MMA(1, 0, At, B0); PG8_MMA(1, 1, At, B1); PG8_BAR; PG8_SCHED;
;             PG8_LDB(B0, 1, 0); PG8_LDB(B1, 1, 1); PG8_SCHED; PG8_LDA(At, 1, 0); PG8_STAGE(PG8_SA(0, 1), a2 + hstepA, voffA);
;             PG8_WAIT_V(8); PG8_WAIT_L(0); PG8_BAR; PG8_MMA(0, 0, At, B0); PG8_MMA(0, 1, At, B1); PG8_BAR; PG8_SCHED;
	v_mfma_f32_16x16x32_bf16 v[84:87], v[132:135], v[164:167], v[84:87]
	v_mfma_f32_16x16x32_bf16 v[76:79], v[140:143], v[164:167], v[76:79]
	v_mfma_f32_16x16x32_bf16 v[72:75], v[132:135], v[172:175], v[72:75]
	v_mfma_f32_16x16x32_bf16 v[68:71], v[140:143], v[172:175], v[68:71]
	v_mfma_f32_16x16x32_bf16 v[60:63], v[132:135], v[180:183], v[60:63]
	v_mfma_f32_16x16x32_bf16 v[56:59], v[140:143], v[180:183], v[56:59]
	v_mfma_f32_16x16x32_bf16 v[48:51], v[132:135], v[188:191], v[48:51]
	v_mfma_f32_16x16x32_bf16 v[44:47], v[140:143], v[188:191], v[44:47]
	v_mfma_f32_16x16x32_bf16 v[84:87], v[136:139], v[168:171], v[84:87]
	v_mfma_f32_16x16x32_bf16 v[76:79], v[144:147], v[168:171], v[76:79]
	v_mfma_f32_16x16x32_bf16 v[72:75], v[136:139], v[176:179], v[72:75]
	v_mfma_f32_16x16x32_bf16 v[68:71], v[144:147], v[176:179], v[68:71]
	v_mfma_f32_16x16x32_bf16 v[60:63], v[136:139], v[184:187], v[60:63]
	v_mfma_f32_16x16x32_bf16 v[56:59], v[144:147], v[184:187], v[56:59]
	v_mfma_f32_16x16x32_bf16 v[48:51], v[136:139], v[192:195], v[48:51]
	v_mfma_f32_16x16x32_bf16 v[44:47], v[144:147], v[192:195], v[44:47]
	v_mfma_f32_16x16x32_bf16 v[40:43], v[148:151], v[164:167], v[40:43]
	v_mfma_f32_16x16x32_bf16 v[36:39], v[156:159], v[164:167], v[36:39]
	v_mfma_f32_16x16x32_bf16 v[28:31], v[148:151], v[172:175], v[28:31]
	v_mfma_f32_16x16x32_bf16 v[24:27], v[156:159], v[172:175], v[24:27]
	v_mfma_f32_16x16x32_bf16 v[16:19], v[148:151], v[180:183], v[16:19]
	v_mfma_f32_16x16x32_bf16 v[12:15], v[156:159], v[180:183], v[12:15]
	v_mfma_f32_16x16x32_bf16 v[8:11], v[148:151], v[188:191], v[8:11]
	v_mfma_f32_16x16x32_bf16 v[4:7], v[156:159], v[188:191], v[4:7]
	v_mfma_f32_16x16x32_bf16 v[40:43], v[152:155], v[168:171], v[40:43]
	v_mfma_f32_16x16x32_bf16 v[36:39], v[160:163], v[168:171], v[36:39]
	v_mfma_f32_16x16x32_bf16 v[28:31], v[152:155], v[176:179], v[28:31]
	v_mfma_f32_16x16x32_bf16 v[24:27], v[160:163], v[176:179], v[24:27]
	v_mfma_f32_16x16x32_bf16 v[16:19], v[152:155], v[184:187], v[16:19]
	v_mfma_f32_16x16x32_bf16 v[12:15], v[160:163], v[184:187], v[12:15]
	v_mfma_f32_16x16x32_bf16 v[8:11], v[152:155], v[192:195], v[8:11]
	v_mfma_f32_16x16x32_bf16 v[4:7], v[160:163], v[192:195], v[4:7]
	s_barrier
	ds_read_b128 v[132:135], v248 offset:32768
	ds_read_b128 v[136:139], v248 offset:33792
	ds_read_b128 v[140:143], v248 offset:34816
	ds_read_b128 v[144:147], v248 offset:35840
	ds_read_b128 v[148:151], v248 offset:49152
	ds_read_b128 v[152:155], v248 offset:50176
	ds_read_b128 v[156:159], v248 offset:51200
	ds_read_b128 v[160:163], v248 offset:52224
	s_add_u32 s30, s30, 0x2b0000
	s_addc_u32 s31, s31, 0
	s_mov_b32 m0, s62
	ds_read_b128 v[164:167], v247 offset:32768
	ds_read_b128 v[168:171], v247 offset:33792
	ds_read_b128 v[172:175], v247 offset:34816
	ds_read_b128 v[176:179], v247 offset:35840
	ds_read_b128 v[180:183], v247 offset:36864
	ds_read_b128 v[184:187], v247 offset:37888
	ds_read_b128 v[188:191], v247 offset:38912
	ds_read_b128 v[192:195], v247 offset:39936
	global_load_lds_dwordx4 v200, s[30:31]
	s_mov_b32 m0, s63
	s_nop 0
	global_load_lds_dwordx4 v204, s[30:31]
	s_waitcnt vmcnt(8)
	s_waitcnt lgkmcnt(0)
	s_barrier
	v_mfma_f32_16x16x32_bf16 v[128:131], v[132:135], v[164:167], v[128:131]
	v_mfma_f32_16x16x32_bf16 v[124:127], v[140:143], v[164:167], v[124:127]
	v_mfma_f32_16x16x32_bf16 v[120:123], v[132:135], v[172:175], v[120:123]
	v_mfma_f32_16x16x32_bf16 v[116:119], v[140:143], v[172:175], v[116:119]
	v_mfma_f32_16x16x32_bf16 v[112:115], v[132:135], v[180:183], v[112:115]
	v_mfma_f32_16x16x32_bf16 v[108:111], v[140:143], v[180:183], v[108:111]
	v_mfma_f32_16x16x32_bf16 v[104:107], v[132:135], v[188:191], v[104:107]
	v_mfma_f32_16x16x32_bf16 v[100:103], v[140:143], v[188:191], v[100:103]
	v_mfma_f32_16x16x32_bf16 v[128:131], v[136:139], v[168:171], v[128:131]
	v_mfma_f32_16x16x32_bf16 v[124:127], v[144:147], v[168:171], v[124:127]
	v_mfma_f32_16x16x32_bf16 v[120:123], v[136:139], v[176:179], v[120:123]
	v_mfma_f32_16x16x32_bf16 v[116:119], v[144:147], v[176:179], v[116:119]
	v_mfma_f32_16x16x32_bf16 v[112:115], v[136:139], v[184:187], v[112:115]
	v_mfma_f32_16x16x32_bf16 v[108:111], v[144:147], v[184:187], v[108:111]
	v_mfma_f32_16x16x32_bf16 v[104:107], v[136:139], v[192:195], v[104:107]
	v_mfma_f32_16x16x32_bf16 v[100:103], v[144:147], v[192:195], v[100:103]
	v_mfma_f32_16x16x32_bf16 v[96:99], v[148:151], v[164:167], v[96:99]
	v_mfma_f32_16x16x32_bf16 v[92:95], v[156:159], v[164:167], v[92:95]
	v_mfma_f32_16x16x32_bf16 v[88:91], v[148:151], v[172:175], v[88:91]
	v_mfma_f32_16x16x32_bf16 v[80:83], v[156:159], v[172:175], v[80:83]
	v_mfma_f32_16x16x32_bf16 v[64:67], v[148:151], v[180:183], v[64:67]
	v_mfma_f32_16x16x32_bf16 v[52:55], v[156:159], v[180:183], v[52:55]
	v_mfma_f32_16x16x32_bf16 v[32:35], v[148:151], v[188:191], v[32:35]
	v_mfma_f32_16x16x32_bf16 v[20:23], v[156:159], v[188:191], v[20:23]
	v_mfma_f32_16x16x32_bf16 v[96:99], v[152:155], v[168:171], v[96:99]
	v_mfma_f32_16x16x32_bf16 v[92:95], v[160:163], v[168:171], v[92:95]
	v_mfma_f32_16x16x32_bf16 v[88:91], v[152:155], v[176:179], v[88:91]
	v_mfma_f32_16x16x32_bf16 v[80:83], v[160:163], v[176:179], v[80:83]
	v_mfma_f32_16x16x32_bf16 v[64:67], v[152:155], v[184:187], v[64:67]
	v_mfma_f32_16x16x32_bf16 v[52:55], v[160:163], v[184:187], v[52:55]
	v_mfma_f32_16x16x32_bf16 v[32:35], v[152:155], v[192:195], v[32:35]
	v_mfma_f32_16x16x32_bf16 v[20:23], v[160:163], v[192:195], v[20:23]
	s_barrier
;     __device__ __forceinline__ int nt(const Unit& u) const { return (u.pn >> 1) < 2 ? 22 : 20; }
; #define PG8_STAGE(bufoff, gbase, voff) do { _Pragma("unroll") for (int _i = 0; _i < 2; ++_i) \
;         __builtin_amdgcn_global_load_lds((const unsigned*)((const char*)(gbase) + (voff)[_i]), (LAS unsigned*)(lds + (bufoff) + ldsw + _i * 8192), 16, 0, 0); } while (0)
; #define PG8_LDA(dst, b, h) do { _Pragma("unroll") for (int m = 0; m < 4; ++m) _Pragma("unroll") for (int k = 0; k < 2; ++k) dst[m][k] = *(const LAS bf16x8*)(pA + PG8_SA(b, h) + m * 2048 + k * 1024); } while (0)
; #define PG8_MMA(ai, bj, At, Bt) do { __builtin_amdgcn_s_setprio(1); _Pragma("unroll") for (int m = 0; m < 4; ++m) _Pragma("unroll") for (int n = 0; n < 2; ++n) _Pragma("unroll") for (int k = 0; k < 2; ++k) \
;         acc[ai][bj][m][n] = __builtin_amdgcn_mfma_f32_16x16x32_bf16(Bt[n][k], At[m][k], acc[ai][bj][m][n], 0, 0, 0); __builtin_amdgcn_s_setprio(0); } while (0)
; #define PG8_WAIT_V(n) asm volatile("s_waitcnt vmcnt(" #n ")" ::: "memory")
; #define PG8_WAIT_L(n) asm volatile("s_waitcnt lgkmcnt(" #n ")" ::: "memory")
; #define PG8_BAR __builtin_amdgcn_s_barrier()
; #define PG8_SCHED __builtin_amdgcn_sched_barrier(0)
; template <class Desc, class Epi, bool ALIGN_EPI>
; __device__ __forceinline__ void gemm_phase(LAS unsigned char* lds, const Desc& D, const Epi& E, int G, int c) {
;     ...
;         for (int t = 0; t < nt; t += 2) {
;     ...
;             PG8_LDA(At, 1, 1); PG8_STAGE(PG8_SB(1, 0), b3, voffB); PG8_STAGE(PG8_SB(1, 1), b3 + hstepB, voffB); PG8_STAGE(PG8_SA(1, 0), a3, voffA);
;             PG8_WAIT_V(8); PG8_WAIT_L(0); PG8_BAR; PG8_MMA(1, 0, At, B0); PG8_MMA(1, 1, At, B1); PG8_BAR; PG8_SCHED;
	s_mov_b32 m0, s64
	s_add_u32 s40, s20, 0x80
	s_addc_u32 s41, s21, 0
	s_add_u32 s20, s20, 0x2b0080
	s_addc_u32 s21, s21, 0
	ds_read_b128 v[164:167], v247 offset:49152
	ds_read_b128 v[168:171], v247 offset:50176
	ds_read_b128 v[172:175], v247 offset:51200
	ds_read_b128 v[176:179], v247 offset:52224
	ds_read_b128 v[180:183], v247 offset:53248
	ds_read_b128 v[184:187], v247 offset:54272
	ds_read_b128 v[188:191], v247 offset:55296
	ds_read_b128 v[192:195], v247 offset:56320
	global_load_lds_dwordx4 v202, s[40:41]
	s_mov_b32 m0, s65
	s_nop 0
	global_load_lds_dwordx4 v206, s[40:41]
	s_mov_b32 m0, s69
	s_nop 0
	global_load_lds_dwordx4 v202, s[20:21]
	s_mov_b32 m0, s70
	s_nop 0
	global_load_lds_dwordx4 v206, s[20:21]
	s_sub_u32 s42, s30, 0x2aff80
	s_subb_u32 s43, s31, 0
	s_mov_b32 m0, s66
	s_nop 0
	global_load_lds_dwordx4 v200, s[42:43]
	s_mov_b32 m0, s67
	s_nop 0
	global_load_lds_dwordx4 v204, s[42:43]
	s_waitcnt vmcnt(8)
	s_waitcnt lgkmcnt(0)
	s_barrier
	v_mfma_f32_16x16x32_bf16 v[84:87], v[132:135], v[164:167], v[84:87]
	v_mfma_f32_16x16x32_bf16 v[76:79], v[140:143], v[164:167], v[76:79]
	v_mfma_f32_16x16x32_bf16 v[72:75], v[132:135], v[172:175], v[72:75]
	v_mfma_f32_16x16x32_bf16 v[68:71], v[140:143], v[172:175], v[68:71]
	v_mfma_f32_16x16x32_bf16 v[60:63], v[132:135], v[180:183], v[60:63]
	v_mfma_f32_16x16x32_bf16 v[56:59], v[140:143], v[180:183], v[56:59]
	v_mfma_f32_16x16x32_bf16 v[48:51], v[132:135], v[188:191], v[48:51]
	v_mfma_f32_16x16x32_bf16 v[44:47], v[140:143], v[188:191], v[44:47]
	v_mfma_f32_16x16x32_bf16 v[84:87], v[136:139], v[168:171], v[84:87]
	v_mfma_f32_16x16x32_bf16 v[76:79], v[144:147], v[168:171], v[76:79]
	v_mfma_f32_16x16x32_bf16 v[72:75], v[136:139], v[176:179], v[72:75]
	v_mfma_f32_16x16x32_bf16 v[68:71], v[144:147], v[176:179], v[68:71]
	v_mfma_f32_16x16x32_bf16 v[60:63], v[136:139], v[184:187], v[60:63]
	v_mfma_f32_16x16x32_bf16 v[56:59], v[144:147], v[184:187], v[56:59]
	v_mfma_f32_16x16x32_bf16 v[48:51], v[136:139], v[192:195], v[48:51]
	v_mfma_f32_16x16x32_bf16 v[44:47], v[144:147], v[192:195], v[44:47]
	v_mfma_f32_16x16x32_bf16 v[40:43], v[148:151], v[164:167], v[40:43]
	v_mfma_f32_16x16x32_bf16 v[36:39], v[156:159], v[164:167], v[36:39]
	v_mfma_f32_16x16x32_bf16 v[28:31], v[148:151], v[172:175], v[28:31]
	v_mfma_f32_16x16x32_bf16 v[24:27], v[156:159], v[172:175], v[24:27]
	v_mfma_f32_16x16x32_bf16 v[16:19], v[148:151], v[180:183], v[16:19]
	v_mfma_f32_16x16x32_bf16 v[12:15], v[156:159], v[180:183], v[12:15]
	v_mfma_f32_16x16x32_bf16 v[8:11], v[148:151], v[188:191], v[8:11]
	v_mfma_f32_16x16x32_bf16 v[4:7], v[156:159], v[188:191], v[4:7]
	v_mfma_f32_16x16x32_bf16 v[40:43], v[152:155], v[168:171], v[40:43]
	v_mfma_f32_16x16x32_bf16 v[36:39], v[160:163], v[168:171], v[36:39]
	v_mfma_f32_16x16x32_bf16 v[28:31], v[152:155], v[176:179], v[28:31]
	v_mfma_f32_16x16x32_bf16 v[24:27], v[160:163], v[176:179], v[24:27]
	v_mfma_f32_16x16x32_bf16 v[16:19], v[152:155], v[184:187], v[16:19]
	v_mfma_f32_16x16x32_bf16 v[12:15], v[160:163], v[184:187], v[12:15]
	v_mfma_f32_16x16x32_bf16 v[8:11], v[152:155], v[192:195], v[8:11]
	v_mfma_f32_16x16x32_bf16 v[4:7], v[160:163], v[192:195], v[4:7]
	s_barrier
	s_cmp_ge_u32 s14, s24
	s_mov_b32 s39, s14
	s_cbranch_scc1 .LBB0_1776
